# P7 load balance: workgroups 32..63 hand the K=1024 half of their prompt tile to 64..95 (flag hand-off); w_ffn_up conversion on workgroups 96..255
# speedup vs baseline: 1.0316x; 1.0042x over previous
;     __device__ __forceinline__ bool next(int i, Unit& u) const {
;         const long L = (long)i * G + c; const int nwg = nM * nN; if (L >= nwg) return false;
;         int wgid = (int)L; { const int q = nwg / 8, r = nwg % 8, xcd = wgid % 8, off = wgid / 8; wgid = (xcd < r ? xcd * (q + 1) : r * (q + 1) + (xcd - r) * q) + off; }
;         const int nig = 8 * nN, gid = wgid / nig, fm = gid * 8, gsz = (nM - fm) < 8 ? (nM - fm) : 8;
;         u.pm = fm + ((wgid % nig) % gsz); u.pn = (wgid % nig) / gsz; u.tag = 0;
;         u.A = A + (size_t)u.pm * a_tile + (size_t)((u.pn >> a_sh) * a_mul); u.B = B + (size_t)u.pn * b_tile; u.nt = nt; return true;
; template <class Epi, class S_t>
; __device__ __forceinline__ void gemm_phase(LAS unsigned char* lds, int lda, int ldb, const S_t& S, const Epi& E) {
;     ...
;     Unit cur, nxt; int ui = 0;
;     if (!S.next(0, cur)) return;
.Lipf_skip_6:
	v_mov_b32_e32 v8, v212
	s_waitcnt lgkmcnt(0)
	v_cndmask_b32_e64 v0, 0, 1, s[56:57]
	s_barrier
	v_cmp_ne_u32_e64 s[82:83], 1, v0
	s_andn2_b64 vcc, exec, s[56:57]
	v_readfirstlane_b32 s4, v8
	s_cbranch_vccnz .LBB0_953
	s_sub_i32 s98, s2, 32
	s_cmp_lt_u32 s98, 32
	s_cbranch_scc1 .LBB0_953
	s_sub_i32 s98, s2, 64
	s_cmp_lt_u32 s98, 32
	s_cbranch_scc0 .Lp7x_entry
	s_sub_i32 s2, s2, 32
.Lp7x_entry:
	s_ashr_i32 s0, s2, 31
	s_lshr_b32 s0, s0, 29
	s_add_i32 s5, s2, s0
	s_and_b32 s0, s5, -8
	s_sub_i32 s6, s2, s0
	s_cmp_gt_i32 s6, -1
	s_cbranch_scc0 .LBB0_935
	s_lshl_b32 s8, s6, 5
	s_cbranch_execz .LBB0_936
	s_branch .LBB0_937

; #define PG8_WAIT_V(n) asm volatile("s_waitcnt vmcnt(" #n ")" ::: "memory")
; #define PG8_BAR __builtin_amdgcn_s_barrier()
; template <class Epi, class S_t>
; __device__ __forceinline__ void gemm_phase(LAS unsigned char* lds, int lda, int ldb, const S_t& S, const Epi& E) {
;     ...
;         if (!has_next) break;
; #pragma unroll
;         for (int a = 0; a < 2; ++a)
; #pragma unroll
;             for (int b = 0; b < 2; ++b)
; #pragma unroll
;                 for (int m = 0; m < 4; ++m)
; #pragma unroll
;                     for (int n = 0; n < 2; ++n) acc[a][b][m][n] = (f32x4){0.f, 0.f, 0.f, 0.f};
;         cur = nxt; cA = nA; cB = nB; ++ui;
;     }
;     PG8_WAIT_V(0);
;     if (wr == 0) PG8_BAR;
;     PG8_BAR;
; __global__ void __launch_bounds__(NTHREADS, 2) fwd_megakernel(Params p) {
;     ...
;         { SchedP7 S{Sched{(const char*)(ws + WS_YP), (const char*)(ws + WS_WPU), TA * PW, TA * PW, 32, DM / 256, PW / 64, G, c, 0, 0}, 0, 1000};
;           EpiMerge<false> E{(bf16_t*)(ws + WS_MG), (const bf16_t*)(ws + WS_Z), PW + LW, (unsigned*)(ws + WS_BAR)};
;           gemm_phase(lds, PW, PW, S, E); }
.LBB0_953:
	v_readfirstlane_b32 s98, v210
	s_lshr_b32 s98, s98, 3
	s_cmp_eq_u32 s98, s2
	s_cbranch_scc1 .Lp7x_done
	buffer_wbl2 sc1
	s_waitcnt vmcnt(0)
	v_readlane_b32 s100, v255, 1
	v_readlane_b32 s101, v255, 2
	s_sub_i32 s99, s2, 32
	s_lshl_b32 s99, s99, 6
	s_addk_i32 s99, 0x1c00
	s_mov_b32 s2, s98
	v_mov_b32_e32 v128, s99
	v_mov_b32_e32 v129, 1
	s_mov_b64 s[98:99], exec
	s_mov_b64 exec, 1
	s_nop 4
	global_atomic_add v128, v129, s[100:101]
	s_mov_b64 exec, s[98:99]
	s_add_u32 s46, s84, 0x19100000
	s_addc_u32 s47, s85, 0
	v_mov_b32_e32 v8, v212
	s_branch .Lp7x_entry

; #define PG8_STAGE(bufoff, gbase, voff) do { _Pragma("unroll") for (int _i = 0; _i < 2; ++_i) \
;         __builtin_amdgcn_global_load_lds((const unsigned*)((const char*)(gbase) + (voff)[_i]), (LAS unsigned*)(lds + (bufoff) + ldsw + _i * 8192), 16, 0, 0); } while (0)
; #define PG8_LDA(dst, b, h) do { _Pragma("unroll") for (int m = 0; m < 4; ++m) _Pragma("unroll") for (int k = 0; k < 2; ++k) dst[m][k] = *(const LAS bf16x8*)(lds + PG8_SA(b, h) + aoff + m * 2048 + k * 1024); } while (0)
; #define PG8_LDB(dst, b, h) do { _Pragma("unroll") for (int n = 0; n < 2; ++n) _Pragma("unroll") for (int k = 0; k < 2; ++k) dst[n][k] = *(const LAS bf16x8*)(lds + PG8_SB(b, h) + boff + n * 2048 + k * 1024); } while (0)
; #define PG8_WAIT_V(n) asm volatile("s_waitcnt vmcnt(" #n ")" ::: "memory")
; #define PG8_WAIT_L(n) asm volatile("s_waitcnt lgkmcnt(" #n ")" ::: "memory")
; #define PG8_BAR __builtin_amdgcn_s_barrier()
; #define PG8_SCHED __builtin_amdgcn_sched_barrier(0)
; template <class Epi, class S_t>
; __device__ __forceinline__ void gemm_phase(LAS unsigned char* lds, int lda, int ldb, const S_t& S, const Epi& E) {
;     ...
;             PG8_LDB(B0, 0, 0); PG8_SCHED; PG8_LDA(At, 0, 0); PG8_STAGE(PG8_SA(1, 1), a1 + hstepA, voffA);
;             PG8_WAIT_L(8); PG8_BAR; PG8_WAIT_L(0); PG8_MMA(0, 0, At, B0); PG8_BAR; PG8_SCHED;
;             PG8_LDB(B1, 0, 1); PG8_STAGE(PG8_SB(0, 0), b2, voffB);
;             PG8_BAR; PG8_WAIT_L(0); PG8_MMA(0, 1, At, B1); PG8_BAR;
;             PG8_LDA(At, 0, 1); PG8_STAGE(PG8_SA(0, 0), a2, voffA);
;             PG8_BAR; PG8_WAIT_L(0); PG8_MMA(1, 0, At, B0); PG8_BAR; PG8_SCHED;
;             PG8_STAGE(PG8_SB(0, 1), b2 + hstepB, voffB);
;             PG8_WAIT_V(6); PG8_BAR; PG8_MMA(1, 1, At, B1); PG8_BAR;
;             PG8_LDB(B0, 1, 0); PG8_SCHED; PG8_LDA(At, 1, 0); PG8_STAGE(PG8_SA(0, 1), a2 + hstepA, voffA);
;             PG8_WAIT_L(8); PG8_BAR; PG8_WAIT_L(0); PG8_MMA(0, 0, At, B0); PG8_BAR; PG8_SCHED;
;             PG8_LDB(B1, 1, 1); PG8_STAGE(PG8_SB(1, 0), b3, voffB);
;             PG8_BAR; PG8_WAIT_L(0); PG8_MMA(0, 1, At, B1); PG8_BAR;
;             PG8_LDA(At, 1, 1); PG8_STAGE(PG8_SA(1, 0), a3, voffA);
;             PG8_BAR; PG8_WAIT_L(0); PG8_MMA(1, 0, At, B0); PG8_BAR; PG8_SCHED;
;             PG8_STAGE(PG8_SB(1, 1), b3 + hstepB, voffB);
;             PG8_WAIT_V(6); PG8_BAR; PG8_MMA(1, 1, At, B1); PG8_BAR;
.LBB0_966:
	ds_read_b128 v[128:131], v169
	ds_read_b128 v[132:135], v169 offset:1024
	ds_read_b128 v[136:139], v169 offset:2048
	ds_read_b128 v[140:143], v169 offset:3072
	s_add_u32 s33, s56, 0xfff80080
	s_addc_u32 s58, s57, -1
	s_cmp_eq_u32 s43, 28
	s_cselect_b32 s61, s55, s58
	s_cselect_b32 s60, s54, s33
	s_cselect_b32 s59, s49, s1
	s_cselect_b32 s58, s48, s0
	s_add_i32 m0, s16, 0xc000
	ds_read_b128 v[156:159], v170
	ds_read_b128 v[160:163], v170 offset:1024
	ds_read_b128 v[172:175], v170 offset:2048
	ds_read_b128 v[176:179], v170 offset:3072
	ds_read_b128 v[180:183], v170 offset:4096
	ds_read_b128 v[186:189], v170 offset:5120
	ds_read_b128 v[190:193], v170 offset:6144
	ds_read_b128 v[194:197], v170 offset:7168
	global_load_lds_dwordx4 v152, s[56:57]
	s_add_i32 m0, s16, 0xe000
	s_nop 0
	global_load_lds_dwordx4 v154, s[56:57]
	s_waitcnt lgkmcnt(8)
	s_barrier
	s_waitcnt lgkmcnt(0)
	s_setprio 1
	s_waitcnt lgkmcnt(0)
	v_mfma_f32_16x16x32_bf16 v[124:127], v[128:131], v[156:159], v[124:127]
	v_mfma_f32_16x16x32_bf16 v[120:123], v[136:139], v[156:159], v[120:123]
	v_mfma_f32_16x16x32_bf16 v[108:111], v[128:131], v[172:175], v[108:111]
	v_mfma_f32_16x16x32_bf16 v[104:107], v[136:139], v[172:175], v[104:107]
	v_mfma_f32_16x16x32_bf16 v[92:95], v[128:131], v[180:183], v[92:95]
	v_mfma_f32_16x16x32_bf16 v[88:91], v[136:139], v[180:183], v[88:91]
	v_mfma_f32_16x16x32_bf16 v[76:79], v[128:131], v[190:193], v[76:79]
	v_mfma_f32_16x16x32_bf16 v[72:75], v[136:139], v[190:193], v[72:75]
	v_mfma_f32_16x16x32_bf16 v[124:127], v[132:135], v[160:163], v[124:127]
	v_mfma_f32_16x16x32_bf16 v[120:123], v[140:143], v[160:163], v[120:123]
	v_mfma_f32_16x16x32_bf16 v[108:111], v[132:135], v[176:179], v[108:111]
	v_mfma_f32_16x16x32_bf16 v[104:107], v[140:143], v[176:179], v[104:107]
	v_mfma_f32_16x16x32_bf16 v[92:95], v[132:135], v[186:189], v[92:95]
	v_mfma_f32_16x16x32_bf16 v[88:91], v[140:143], v[186:189], v[88:91]
	v_mfma_f32_16x16x32_bf16 v[76:79], v[132:135], v[194:197], v[76:79]
	v_mfma_f32_16x16x32_bf16 v[72:75], v[140:143], v[194:197], v[72:75]
	s_setprio 0
	s_barrier
	s_add_i32 s33, s88, s5
	s_add_u32 s98, s58, s8
	s_addc_u32 s99, s59, s9
	s_mov_b32 m0, s33
	ds_read_b128 v[198:201], v171
	ds_read_b128 v[202:205], v171 offset:1024
	ds_read_b128 v[206:209], v171 offset:2048
	ds_read_b128 v[222:225], v171 offset:3072
	global_load_lds_dwordx4 v146, s[58:59]
	s_add_i32 m0, s33, 0x2000
	s_nop 0
	global_load_lds_dwordx4 v150, s[58:59]
	s_barrier
	s_waitcnt lgkmcnt(0)
	s_setprio 1
	s_waitcnt lgkmcnt(0)
	v_mfma_f32_16x16x32_bf16 v[116:119], v[198:201], v[156:159], v[116:119]
	v_mfma_f32_16x16x32_bf16 v[112:115], v[206:209], v[156:159], v[112:115]
	v_mfma_f32_16x16x32_bf16 v[100:103], v[198:201], v[172:175], v[100:103]
	v_mfma_f32_16x16x32_bf16 v[96:99], v[206:209], v[172:175], v[96:99]
	v_mfma_f32_16x16x32_bf16 v[84:87], v[198:201], v[180:183], v[84:87]
	v_mfma_f32_16x16x32_bf16 v[80:83], v[206:209], v[180:183], v[80:83]
	v_mfma_f32_16x16x32_bf16 v[68:71], v[198:201], v[190:193], v[68:71]
	v_mfma_f32_16x16x32_bf16 v[64:67], v[206:209], v[190:193], v[64:67]
	v_mfma_f32_16x16x32_bf16 v[116:119], v[202:205], v[160:163], v[116:119]
	v_mfma_f32_16x16x32_bf16 v[112:115], v[222:225], v[160:163], v[112:115]
	v_mfma_f32_16x16x32_bf16 v[100:103], v[202:205], v[176:179], v[100:103]
	v_mfma_f32_16x16x32_bf16 v[96:99], v[222:225], v[176:179], v[96:99]
	v_mfma_f32_16x16x32_bf16 v[84:87], v[202:205], v[186:189], v[84:87]
	v_mfma_f32_16x16x32_bf16 v[80:83], v[222:225], v[186:189], v[80:83]
	v_mfma_f32_16x16x32_bf16 v[68:71], v[202:205], v[194:197], v[68:71]
	v_mfma_f32_16x16x32_bf16 v[64:67], v[222:225], v[194:197], v[64:67]
	s_setprio 0
	s_mov_b32 m0, s16
	s_add_u32 s100, s60, s8
	s_addc_u32 s101, s61, s9
	s_barrier
	ds_read_b128 v[156:159], v170 offset:16384
	ds_read_b128 v[160:163], v170 offset:17408
	ds_read_b128 v[172:175], v170 offset:18432
	ds_read_b128 v[176:179], v170 offset:19456
	ds_read_b128 v[180:183], v170 offset:20480
	ds_read_b128 v[186:189], v170 offset:21504
	ds_read_b128 v[190:193], v170 offset:22528
	ds_read_b128 v[194:197], v170 offset:23552
	global_load_lds_dwordx4 v144, s[60:61]
	s_mov_b32 m0, s17
	s_nop 0
	global_load_lds_dwordx4 v148, s[60:61]
	s_barrier
	s_waitcnt lgkmcnt(0)
	s_setprio 1
	s_waitcnt lgkmcnt(0)
	v_mfma_f32_16x16x32_bf16 v[60:63], v[128:131], v[156:159], v[60:63]
	v_mfma_f32_16x16x32_bf16 v[56:59], v[136:139], v[156:159], v[56:59]
	v_mfma_f32_16x16x32_bf16 v[44:47], v[128:131], v[172:175], v[44:47]
	v_mfma_f32_16x16x32_bf16 v[40:43], v[136:139], v[172:175], v[40:43]
	v_mfma_f32_16x16x32_bf16 v[28:31], v[128:131], v[180:183], v[28:31]
	v_mfma_f32_16x16x32_bf16 v[24:27], v[136:139], v[180:183], v[24:27]
	v_mfma_f32_16x16x32_bf16 v[12:15], v[128:131], v[190:193], v[12:15]
	v_mfma_f32_16x16x32_bf16 v[8:11], v[136:139], v[190:193], v[8:11]
	v_mfma_f32_16x16x32_bf16 v[60:63], v[132:135], v[160:163], v[60:63]
	v_mfma_f32_16x16x32_bf16 v[56:59], v[140:143], v[160:163], v[56:59]
	v_mfma_f32_16x16x32_bf16 v[44:47], v[132:135], v[176:179], v[44:47]
	v_mfma_f32_16x16x32_bf16 v[40:43], v[140:143], v[176:179], v[40:43]
	v_mfma_f32_16x16x32_bf16 v[28:31], v[132:135], v[186:189], v[28:31]
	v_mfma_f32_16x16x32_bf16 v[24:27], v[140:143], v[186:189], v[24:27]
	v_mfma_f32_16x16x32_bf16 v[12:15], v[132:135], v[194:197], v[12:15]
	v_mfma_f32_16x16x32_bf16 v[8:11], v[140:143], v[194:197], v[8:11]
	s_setprio 0
	s_barrier
	s_add_u32 s64, s58, 0x80000
	s_addc_u32 s65, s59, 0
	s_add_i32 s33, s89, s5
	s_mov_b32 m0, s33
	s_nop 0
	global_load_lds_dwordx4 v146, s[64:65]
	s_add_i32 m0, s33, 0x2000
	s_nop 0
	global_load_lds_dwordx4 v150, s[64:65]
	s_waitcnt vmcnt(6)
	s_barrier
; #define PG8_STAGE(bufoff, gbase, voff) do { _Pragma("unroll") for (int _i = 0; _i < 2; ++_i) \
;         __builtin_amdgcn_global_load_lds((const unsigned*)((const char*)(gbase) + (voff)[_i]), (LAS unsigned*)(lds + (bufoff) + ldsw + _i * 8192), 16, 0, 0); } while (0)
; #define PG8_LDA(dst, b, h) do { _Pragma("unroll") for (int m = 0; m < 4; ++m) _Pragma("unroll") for (int k = 0; k < 2; ++k) dst[m][k] = *(const LAS bf16x8*)(lds + PG8_SA(b, h) + aoff + m * 2048 + k * 1024); } while (0)
; #define PG8_LDB(dst, b, h) do { _Pragma("unroll") for (int n = 0; n < 2; ++n) _Pragma("unroll") for (int k = 0; k < 2; ++k) dst[n][k] = *(const LAS bf16x8*)(lds + PG8_SB(b, h) + boff + n * 2048 + k * 1024); } while (0)
; #define PG8_WAIT_V(n) asm volatile("s_waitcnt vmcnt(" #n ")" ::: "memory")
; #define PG8_WAIT_L(n) asm volatile("s_waitcnt lgkmcnt(" #n ")" ::: "memory")
; #define PG8_BAR __builtin_amdgcn_s_barrier()
; #define PG8_SCHED __builtin_amdgcn_sched_barrier(0)
; template <class Epi, class S_t>
; __device__ __forceinline__ void gemm_phase(LAS unsigned char* lds, int lda, int ldb, const S_t& S, const Epi& E) {
;     ...
;             PG8_LDB(B0, 0, 0); PG8_SCHED; PG8_LDA(At, 0, 0); PG8_STAGE(PG8_SA(1, 1), a1 + hstepA, voffA);
;             PG8_WAIT_L(8); PG8_BAR; PG8_WAIT_L(0); PG8_MMA(0, 0, At, B0); PG8_BAR; PG8_SCHED;
;             PG8_LDB(B1, 0, 1); PG8_STAGE(PG8_SB(0, 0), b2, voffB);
;             PG8_BAR; PG8_WAIT_L(0); PG8_MMA(0, 1, At, B1); PG8_BAR;
;             PG8_LDA(At, 0, 1); PG8_STAGE(PG8_SA(0, 0), a2, voffA);
;             PG8_BAR; PG8_WAIT_L(0); PG8_MMA(1, 0, At, B0); PG8_BAR; PG8_SCHED;
;             PG8_STAGE(PG8_SB(0, 1), b2 + hstepB, voffB);
;             PG8_WAIT_V(6); PG8_BAR; PG8_MMA(1, 1, At, B1); PG8_BAR;
;             PG8_LDB(B0, 1, 0); PG8_SCHED; PG8_LDA(At, 1, 0); PG8_STAGE(PG8_SA(0, 1), a2 + hstepA, voffA);
;             PG8_WAIT_L(8); PG8_BAR; PG8_WAIT_L(0); PG8_MMA(0, 0, At, B0); PG8_BAR; PG8_SCHED;
;             PG8_LDB(B1, 1, 1); PG8_STAGE(PG8_SB(1, 0), b3, voffB);
;             PG8_BAR; PG8_WAIT_L(0); PG8_MMA(0, 1, At, B1); PG8_BAR;
;             PG8_LDA(At, 1, 1); PG8_STAGE(PG8_SA(1, 0), a3, voffA);
;             PG8_BAR; PG8_WAIT_L(0); PG8_MMA(1, 0, At, B0); PG8_BAR; PG8_SCHED;
;             PG8_STAGE(PG8_SB(1, 1), b3 + hstepB, voffB);
;             PG8_WAIT_V(6); PG8_BAR; PG8_MMA(1, 1, At, B1); PG8_BAR;
	s_setprio 1
	v_mfma_f32_16x16x32_bf16 v[52:55], v[198:201], v[156:159], v[52:55]
	v_mfma_f32_16x16x32_bf16 v[48:51], v[206:209], v[156:159], v[48:51]
	v_mfma_f32_16x16x32_bf16 v[36:39], v[198:201], v[172:175], v[36:39]
	v_mfma_f32_16x16x32_bf16 v[32:35], v[206:209], v[172:175], v[32:35]
	v_mfma_f32_16x16x32_bf16 v[20:23], v[198:201], v[180:183], v[20:23]
	v_mfma_f32_16x16x32_bf16 v[16:19], v[206:209], v[180:183], v[16:19]
	v_mfma_f32_16x16x32_bf16 v[4:7], v[198:201], v[190:193], v[4:7]
	v_mfma_f32_16x16x32_bf16 v[0:3], v[206:209], v[190:193], v[0:3]
	v_mfma_f32_16x16x32_bf16 v[52:55], v[202:205], v[160:163], v[52:55]
	v_mfma_f32_16x16x32_bf16 v[48:51], v[222:225], v[160:163], v[48:51]
	v_mfma_f32_16x16x32_bf16 v[36:39], v[202:205], v[176:179], v[36:39]
	v_mfma_f32_16x16x32_bf16 v[32:35], v[222:225], v[176:179], v[32:35]
	v_mfma_f32_16x16x32_bf16 v[20:23], v[202:205], v[186:189], v[20:23]
	v_mfma_f32_16x16x32_bf16 v[16:19], v[222:225], v[186:189], v[16:19]
	v_mfma_f32_16x16x32_bf16 v[4:7], v[202:205], v[194:197], v[4:7]
	v_mfma_f32_16x16x32_bf16 v[0:3], v[222:225], v[194:197], v[0:3]
	s_setprio 0
	v_add_u32_e32 v140, s90, v167
	s_barrier
	ds_read_b128 v[128:131], v140
	ds_read_b128 v[132:135], v140 offset:1024
	ds_read_b128 v[136:139], v140 offset:2048
	ds_read_b128 v[140:143], v140 offset:3072
	s_add_u32 s60, s60, 0x80000
	s_addc_u32 s61, s61, 0
	s_mov_b32 m0, s20
	ds_read_b128 v[156:159], v170 offset:32768
	ds_read_b128 v[160:163], v170 offset:33792
	ds_read_b128 v[172:175], v170 offset:34816
	ds_read_b128 v[176:179], v170 offset:35840
	ds_read_b128 v[180:183], v170 offset:36864
	ds_read_b128 v[186:189], v170 offset:37888
	ds_read_b128 v[190:193], v170 offset:38912
	ds_read_b128 v[194:197], v170 offset:39936
	global_load_lds_dwordx4 v144, s[60:61]
	s_mov_b32 m0, s21
	s_nop 0
	global_load_lds_dwordx4 v148, s[60:61]
	s_waitcnt lgkmcnt(8)
	s_barrier
	s_waitcnt lgkmcnt(0)
	s_setprio 1
	s_waitcnt lgkmcnt(0)
	v_mfma_f32_16x16x32_bf16 v[124:127], v[128:131], v[156:159], v[124:127]
	v_mfma_f32_16x16x32_bf16 v[120:123], v[136:139], v[156:159], v[120:123]
	v_mfma_f32_16x16x32_bf16 v[108:111], v[128:131], v[172:175], v[108:111]
	v_mfma_f32_16x16x32_bf16 v[104:107], v[136:139], v[172:175], v[104:107]
	v_mfma_f32_16x16x32_bf16 v[92:95], v[128:131], v[180:183], v[92:95]
	v_mfma_f32_16x16x32_bf16 v[88:91], v[136:139], v[180:183], v[88:91]
	v_mfma_f32_16x16x32_bf16 v[76:79], v[128:131], v[190:193], v[76:79]
	v_mfma_f32_16x16x32_bf16 v[72:75], v[136:139], v[190:193], v[72:75]
	v_mfma_f32_16x16x32_bf16 v[124:127], v[132:135], v[160:163], v[124:127]
	v_mfma_f32_16x16x32_bf16 v[120:123], v[140:143], v[160:163], v[120:123]
	v_mfma_f32_16x16x32_bf16 v[108:111], v[132:135], v[176:179], v[108:111]
	v_mfma_f32_16x16x32_bf16 v[104:107], v[140:143], v[176:179], v[104:107]
	v_mfma_f32_16x16x32_bf16 v[92:95], v[132:135], v[186:189], v[92:95]
	v_mfma_f32_16x16x32_bf16 v[88:91], v[140:143], v[186:189], v[88:91]
	v_mfma_f32_16x16x32_bf16 v[76:79], v[132:135], v[194:197], v[76:79]
	v_mfma_f32_16x16x32_bf16 v[72:75], v[140:143], v[194:197], v[72:75]
	s_setprio 0
	s_barrier
	s_add_i32 s33, s90, s5
	v_add_u32_e32 v185, s91, v167
	s_mov_b32 m0, s33
	ds_read_b128 v[198:201], v185
	ds_read_b128 v[202:205], v185 offset:1024
	ds_read_b128 v[206:209], v185 offset:2048
	ds_read_b128 v[222:225], v185 offset:3072
	global_load_lds_dwordx4 v146, s[98:99]
	s_add_i32 m0, s33, 0x2000
	s_nop 0
	global_load_lds_dwordx4 v150, s[98:99]
	s_barrier
	s_waitcnt lgkmcnt(0)
	s_setprio 1
	s_waitcnt lgkmcnt(0)
	v_mfma_f32_16x16x32_bf16 v[116:119], v[198:201], v[156:159], v[116:119]
	v_mfma_f32_16x16x32_bf16 v[112:115], v[206:209], v[156:159], v[112:115]
	v_mfma_f32_16x16x32_bf16 v[100:103], v[198:201], v[172:175], v[100:103]
	v_mfma_f32_16x16x32_bf16 v[96:99], v[206:209], v[172:175], v[96:99]
	v_mfma_f32_16x16x32_bf16 v[84:87], v[198:201], v[180:183], v[84:87]
	v_mfma_f32_16x16x32_bf16 v[80:83], v[206:209], v[180:183], v[80:83]
	v_mfma_f32_16x16x32_bf16 v[68:71], v[198:201], v[190:193], v[68:71]
	v_mfma_f32_16x16x32_bf16 v[64:67], v[206:209], v[190:193], v[64:67]
	v_mfma_f32_16x16x32_bf16 v[116:119], v[202:205], v[160:163], v[116:119]
	v_mfma_f32_16x16x32_bf16 v[112:115], v[222:225], v[160:163], v[112:115]
	v_mfma_f32_16x16x32_bf16 v[100:103], v[202:205], v[176:179], v[100:103]
	v_mfma_f32_16x16x32_bf16 v[96:99], v[222:225], v[176:179], v[96:99]
	v_mfma_f32_16x16x32_bf16 v[84:87], v[202:205], v[186:189], v[84:87]
	v_mfma_f32_16x16x32_bf16 v[80:83], v[222:225], v[186:189], v[80:83]
	v_mfma_f32_16x16x32_bf16 v[68:71], v[202:205], v[194:197], v[68:71]
	v_mfma_f32_16x16x32_bf16 v[64:67], v[222:225], v[194:197], v[64:67]
	s_setprio 0
	s_mov_b32 m0, s35
	s_barrier
; #define PG8_STAGE(bufoff, gbase, voff) do { _Pragma("unroll") for (int _i = 0; _i < 2; ++_i) \
;         __builtin_amdgcn_global_load_lds((const unsigned*)((const char*)(gbase) + (voff)[_i]), (LAS unsigned*)(lds + (bufoff) + ldsw + _i * 8192), 16, 0, 0); } while (0)
; #define PG8_WAIT_V(n) asm volatile("s_waitcnt vmcnt(" #n ")" ::: "memory")
; #define PG8_WAIT_L(n) asm volatile("s_waitcnt lgkmcnt(" #n ")" ::: "memory")
; template <class Epi, class S_t>
; __device__ __forceinline__ void gemm_phase(LAS unsigned char* lds, int lda, int ldb, const S_t& S, const Epi& E) {
;     ...
;             PG8_LDB(B0, 0, 0); PG8_SCHED; PG8_LDA(At, 0, 0); PG8_STAGE(PG8_SA(1, 1), a1 + hstepA, voffA);
;             PG8_WAIT_L(8); PG8_BAR; PG8_WAIT_L(0); PG8_MMA(0, 0, At, B0); PG8_BAR; PG8_SCHED;
;             PG8_LDB(B1, 0, 1); PG8_STAGE(PG8_SB(0, 0), b2, voffB);
;             PG8_BAR; PG8_WAIT_L(0); PG8_MMA(0, 1, At, B1); PG8_BAR;
;             PG8_LDA(At, 0, 1); PG8_STAGE(PG8_SA(0, 0), a2, voffA);
;             PG8_BAR; PG8_WAIT_L(0); PG8_MMA(1, 0, At, B0); PG8_BAR; PG8_SCHED;
;             PG8_STAGE(PG8_SB(0, 1), b2 + hstepB, voffB);
;             PG8_WAIT_V(6); PG8_BAR; PG8_MMA(1, 1, At, B1); PG8_BAR;
;             PG8_LDB(B0, 1, 0); PG8_SCHED; PG8_LDA(At, 1, 0); PG8_STAGE(PG8_SA(0, 1), a2 + hstepA, voffA);
;             PG8_WAIT_L(8); PG8_BAR; PG8_WAIT_L(0); PG8_MMA(0, 0, At, B0); PG8_BAR; PG8_SCHED;
;             PG8_LDB(B1, 1, 1); PG8_STAGE(PG8_SB(1, 0), b3, voffB);
;             PG8_BAR; PG8_WAIT_L(0); PG8_MMA(0, 1, At, B1); PG8_BAR;
;             PG8_LDA(At, 1, 1); PG8_STAGE(PG8_SA(1, 0), a3, voffA);
;             PG8_BAR; PG8_WAIT_L(0); PG8_MMA(1, 0, At, B0); PG8_BAR; PG8_SCHED;
;             PG8_STAGE(PG8_SB(1, 1), b3 + hstepB, voffB);
;             PG8_WAIT_V(6); PG8_BAR; PG8_MMA(1, 1, At, B1); PG8_BAR;
;     __device__ __forceinline__ void operator()(const f32x4 (&acc)[2][2][4][2], const Unit& u, int wr, int wc, int fr, int fq) const {
;     ...
;         if (ADD && u.tag >= 2000) {
;             unsigned* f = flags + P7_FLAG(u.tag - 2000); unsigned sp = 0;
;             while ((unsigned)__builtin_amdgcn_readfirstlane(__hip_atomic_load(f, __ATOMIC_RELAXED, __HIP_MEMORY_SCOPE_AGENT)) < 8u) { __builtin_amdgcn_s_sleep(2); if (++sp > (1u << 20)) break; }
;             __builtin_amdgcn_fence(__ATOMIC_ACQUIRE, "agent");
;             asm volatile("s_waitcnt vmcnt(0)" ::: "memory");
	ds_read_b128 v[156:159], v170 offset:49152
	ds_read_b128 v[160:163], v170 offset:50176
	ds_read_b128 v[172:175], v170 offset:51200
	ds_read_b128 v[176:179], v170 offset:52224
	ds_read_b128 v[180:183], v170 offset:53248
	ds_read_b128 v[186:189], v170 offset:54272
	ds_read_b128 v[190:193], v170 offset:55296
	ds_read_b128 v[194:197], v170 offset:56320
	global_load_lds_dwordx4 v144, s[100:101]
	s_mov_b32 m0, s47
	s_nop 0
	global_load_lds_dwordx4 v148, s[100:101]
	s_barrier
	s_waitcnt lgkmcnt(0)
	s_setprio 1
	s_waitcnt lgkmcnt(0)
	v_mfma_f32_16x16x32_bf16 v[60:63], v[128:131], v[156:159], v[60:63]
	v_mfma_f32_16x16x32_bf16 v[56:59], v[136:139], v[156:159], v[56:59]
	v_mfma_f32_16x16x32_bf16 v[44:47], v[128:131], v[172:175], v[44:47]
	v_mfma_f32_16x16x32_bf16 v[40:43], v[136:139], v[172:175], v[40:43]
	v_mfma_f32_16x16x32_bf16 v[28:31], v[128:131], v[180:183], v[28:31]
	v_mfma_f32_16x16x32_bf16 v[24:27], v[136:139], v[180:183], v[24:27]
	v_mfma_f32_16x16x32_bf16 v[12:15], v[128:131], v[190:193], v[12:15]
	v_mfma_f32_16x16x32_bf16 v[8:11], v[136:139], v[190:193], v[8:11]
	v_mfma_f32_16x16x32_bf16 v[60:63], v[132:135], v[160:163], v[60:63]
	v_mfma_f32_16x16x32_bf16 v[56:59], v[140:143], v[160:163], v[56:59]
	v_mfma_f32_16x16x32_bf16 v[44:47], v[132:135], v[176:179], v[44:47]
	v_mfma_f32_16x16x32_bf16 v[40:43], v[140:143], v[176:179], v[40:43]
	v_mfma_f32_16x16x32_bf16 v[28:31], v[132:135], v[186:189], v[28:31]
	v_mfma_f32_16x16x32_bf16 v[24:27], v[140:143], v[186:189], v[24:27]
	v_mfma_f32_16x16x32_bf16 v[12:15], v[132:135], v[194:197], v[12:15]
	v_mfma_f32_16x16x32_bf16 v[8:11], v[140:143], v[194:197], v[8:11]
	s_setprio 0
	s_barrier
	s_add_u32 s58, s58, 0x80080
	s_addc_u32 s59, s59, 0
	s_add_i32 s33, s91, s5
	s_mov_b32 m0, s33
	s_nop 0
	global_load_lds_dwordx4 v146, s[58:59]
	s_add_i32 m0, s33, 0x2000
	s_nop 0
	global_load_lds_dwordx4 v150, s[58:59]
	s_waitcnt vmcnt(6)
	s_barrier
	s_setprio 1
	v_mfma_f32_16x16x32_bf16 v[52:55], v[198:201], v[156:159], v[52:55]
	v_mfma_f32_16x16x32_bf16 v[48:51], v[206:209], v[156:159], v[48:51]
	v_mfma_f32_16x16x32_bf16 v[36:39], v[198:201], v[172:175], v[36:39]
	v_mfma_f32_16x16x32_bf16 v[32:35], v[206:209], v[172:175], v[32:35]
	v_mfma_f32_16x16x32_bf16 v[20:23], v[198:201], v[180:183], v[20:23]
	v_mfma_f32_16x16x32_bf16 v[16:19], v[206:209], v[180:183], v[16:19]
	v_mfma_f32_16x16x32_bf16 v[4:7], v[198:201], v[190:193], v[4:7]
	v_mfma_f32_16x16x32_bf16 v[0:3], v[206:209], v[190:193], v[0:3]
	v_mfma_f32_16x16x32_bf16 v[52:55], v[202:205], v[160:163], v[52:55]
	v_mfma_f32_16x16x32_bf16 v[48:51], v[222:225], v[160:163], v[48:51]
	v_mfma_f32_16x16x32_bf16 v[36:39], v[202:205], v[176:179], v[36:39]
	v_mfma_f32_16x16x32_bf16 v[32:35], v[222:225], v[176:179], v[32:35]
	v_mfma_f32_16x16x32_bf16 v[20:23], v[202:205], v[186:189], v[20:23]
	v_mfma_f32_16x16x32_bf16 v[16:19], v[222:225], v[186:189], v[16:19]
	v_mfma_f32_16x16x32_bf16 v[4:7], v[202:205], v[194:197], v[4:7]
	v_mfma_f32_16x16x32_bf16 v[0:3], v[222:225], v[194:197], v[0:3]
	s_setprio 0
	s_add_i32 s43, s43, 2
	s_add_u32 s56, s56, 0x100
	s_addc_u32 s57, s57, 0
	s_add_u32 s0, s0, 0x100
	s_addc_u32 s1, s1, 0
	s_cmp_gt_u32 s43, 29
	s_barrier
	s_cbranch_scc0 .LBB0_966
	s_sub_i32 s98, s2, 32
	s_cmp_lt_u32 s98, 32
	s_cbranch_scc0 .Lp7x_nowait
	v_readlane_b32 s100, v255, 1
	v_readlane_b32 s101, v255, 2
	s_lshl_b32 s98, s98, 6
	s_addk_i32 s98, 0x1c00
	s_add_u32 s100, s100, s98
	s_addc_u32 s101, s101, 0
.Lp7x_poll:
	v_mov_b32_e32 v128, 0
	global_load_dword v128, v128, s[100:101] sc1
	s_waitcnt vmcnt(0)
	v_readfirstlane_b32 s98, v128
	s_cmp_gt_u32 s98, 7
	s_cbranch_scc1 .Lp7x_got
	s_sleep 2
	s_branch .Lp7x_poll

;     __device__ __forceinline__ void operator()(const f32x4 (&acc)[2][2][4][2], const Unit& u, int wr, int wc, int fr, int fq) const {
;     ...
;         if (ADD && u.tag >= 2000) {
;             unsigned* f = flags + P7_FLAG(u.tag - 2000); unsigned sp = 0;
.Lp7x_nowait:
	s_cmpk_lt_i32 s6, 0x7d0
	s_cbranch_scc1 .LBB0_962
	s_lshl_b32 s6, s6, 6
	s_lshl_b64 s[0:1], s[6:7], 2
	v_readlane_b32 s48, v255, 1
	v_readlane_b32 s49, v255, 2
	s_add_u32 s0, s48, s0
	s_addc_u32 s1, s49, s1
	s_add_u32 s0, s0, 0xfff86600
	s_addc_u32 s1, s1, -1
	s_mov_b32 s6, 0x100001
	s_branch .LBB0_970

; #define LAS __attribute__((address_space(3)))
; template <int PART> __device__ __forceinline__ void phase0(const Params& p, LAS unsigned char* lds) {
;     ...
;     const int gw = ((int)blockIdx.x - SKIP) * NWAVES + wave, NGW = ((int)gridDim.x - SKIP) * NWAVES;
;     if (gw < 0) return;
;     const int gt = blockIdx.x * NTHREADS + tid, NGT = gridDim.x * NTHREADS;
;     unsigned char* ws = p.ws;
;     LAS float* scr = (LAS float*)(lds + wave * 16640);
;     constexpr int I0 = 32 * 192, I1 = 32 * 112, I2 = 32 * 192, I3 = 96 * 32, I4 = 32 * 32, I5 = 32 * 32, I6 = 16 * 32, I7 = 64, I8 = 128, I9 = 128;
;     constexpr int NIT = I0 + I1 + I2 + I3 + I4 + I5 + I6 + I7 + I8 + I9;
;     constexpr int U0 = I0 + I1, U1 = U0 + I2 / 2, D0 = I0 + I1 + I2, D1 = D0 + I3;
;     constexpr int CUT = (U1 - U0) + I3;
;     constexpr int LO = PART == 0 ? 0 : PART == 1 ? I0 : PART == 2 ? U0 : D0, HI = PART == 0 ? I0 : PART == 1 ? NIT - CUT : PART == 2 ? U1 : D1;
;     for (int it0 = LO + gw; it0 < HI; it0 += NGW) {
;         int it = it0;
;         if (PART == 1) { if (it >= U0) it += U1 - U0; if (it >= D0) it += I3; }
;         int r = it;
;         if (r < I0) { const int nb = r % 192, kb = r / 192; cvt_item(p.in[I_WADA], NADA, (bf16_t*)(ws + WS_WADA), DM, 64 * kb, 64 * nb, 64 * nb, scr, lane); continue; } r -= I0;
;         if (r < I1) { const int nb = r % 112, kb = r / 112; cvt_item(p.in[I_WIN], INW, (bf16_t*)(ws + WS_WIN), DM, 64 * kb, 64 * nb, 64 * nb, scr, lane); continue; } r -= I1;
;         if (r < I2) { const int nb = r % 192, kb = r / 192; const int n0 = 64 * nb; const int j0 = n0 < DFF ? n0 : n0 - DFF;
;             const int drow = (j0 >> 7) * 256 + (n0 < DFF ? 0 : 128) + (j0 & 127);
;             cvt_item(p.in[I_WUP], 2 * DFF, (bf16_t*)(ws + WS_WUP), DM, 64 * kb, n0, drow, scr, lane); continue; } r -= I2;
.LBB0_975:
	v_readlane_b32 s0, v255, 6
	v_add_u32_e32 v0, 0xfffffa00, v210
	s_add_i32 s34, s0, 0xfffffa00
	s_movk_i32 s0, 0xc00
	v_cmp_gt_u32_e64 s[50:51], s0, v0
	v_add_u32_e32 v0, 0xfffffd00, v210
	v_cmp_gt_u32_e32 vcc, s0, v0
	v_readlane_b32 s99, v255, 6
	s_add_i32 s99, s99, 0xfffffd00
	v_lshrrev_b32_e32 v221, 3, v184
	v_readlane_b32 s1, v255, 7
	s_and_saveexec_b64 s[8:9], vcc
	s_cbranch_execz .LBB0_986
	v_and_b32_e32 v0, 56, v217
	s_movk_i32 s0, 0x4100
	v_mul_u32_u24_e32 v5, 0x104, v0
	v_lshlrev_b32_e32 v0, 1, v0
	v_mov_b32_e32 v1, 0
	v_readlane_b32 s12, v254, 33
	v_mad_u32_u24 v4, v213, s0, 0
	v_lshl_add_u64 v[2:3], s[84:85], 0, v[0:1]
	s_mov_b64 s[0:1], 0x2600000
	v_mov_b32_e32 v219, v1
	v_readlane_b32 s13, v254, 34
	v_readlane_b32 s14, v254, 35
	v_readlane_b32 s15, v254, 36
	v_readlane_b32 s16, v254, 37
	v_readlane_b32 s17, v254, 38
	v_readlane_b32 s18, v254, 39
	v_readlane_b32 s19, v254, 40
	v_readlane_b32 s20, v254, 41
	v_readlane_b32 s21, v254, 42
	v_readlane_b32 s22, v254, 43
	v_readlane_b32 s23, v254, 44
	v_readlane_b32 s24, v254, 45
	v_readlane_b32 s25, v254, 46
	v_readlane_b32 s26, v254, 47
	v_readlane_b32 s27, v254, 48
	v_lshl_add_u64 v[2:3], v[2:3], 0, s[0:1]
	v_readlane_b32 s0, v255, 12
	v_lshl_add_u64 v[8:9], s[18:19], 0, v[218:219]
	v_readlane_b32 s12, v254, 17
	v_lshlrev_b32_e32 v6, 2, v221
	v_readlane_b32 s1, v255, 13
	v_readlane_b32 s13, v254, 18
	v_readlane_b32 s24, v254, 29
	v_readlane_b32 s25, v254, 30
	v_add_u32_e32 v15, 0x2300, v210
	v_add_u32_e32 v22, v4, v218
	v_add3_u32 v23, v4, v5, v6
	v_lshl_add_u64 v[4:5], s[0:1], 0, v[0:1]
	v_readlane_b32 s16, v254, 21
	v_readlane_b32 s17, v254, 22
	v_readlane_b32 s18, v254, 23
	v_readlane_b32 s19, v254, 24
	v_readlane_b32 s20, v254, 25
	v_readlane_b32 s21, v254, 26
	s_mov_b64 s[0:1], s[12:13]
	s_mov_b64 s[12:13], s[24:25]
	v_or_b32_e32 v24, 8, v221
	v_or_b32_e32 v25, 16, v221
	v_or_b32_e32 v26, 24, v221
	v_or_b32_e32 v27, 32, v221
	v_or_b32_e32 v28, 40, v221
	v_or_b32_e32 v29, 48, v221
	v_or_b32_e32 v30, 56, v221
	v_lshl_add_u64 v[6:7], s[44:45], 0, v[0:1]
	v_lshl_add_u64 v[10:11], s[12:13], 0, v[218:219]
	v_lshl_add_u64 v[12:13], s[0:1], 0, v[218:219]
	v_lshlrev_b32_e32 v14, 6, v15
	s_lshl_b32 s0, s99, 6
	s_mov_b32 s1, 0xc000
	s_mov_b32 s4, 0x54000
	s_mov_b32 s5, 0xa8000
	s_mov_b32 s16, 0xfc000
	s_mov_b32 s17, 0x150000
	s_mov_b32 s18, 0x1a4000
	s_mov_b32 s19, 0x1ec000
	s_mov_b32 s20, 0x1f8000
	s_mov_b32 s21, 0x204000
	s_mov_b32 s35, 0x210000
	s_mov_b32 s46, 0x21c000
	s_mov_b32 s47, 0x228000
	s_mov_b32 s48, 0x234000
	s_mov_b32 s49, 0x240000
	s_mov_b32 s52, 0x24c000
	s_mov_b32 s53, 0x258000
	v_mov_b32_e32 v31, 0x80
	v_add_u32_e32 v32, 0x400, v22
	v_add_u32_e32 v33, 0x800, v22
	v_add_u32_e32 v34, 0xc00, v22
	v_add_u32_e32 v35, 0x1000, v22
	v_add_u32_e32 v36, 0x1400, v22
	v_add_u32_e32 v37, 0x1800, v22
	v_add_u32_e32 v38, 0x1c00, v22
	v_add_u32_e32 v39, 0x2000, v22
	v_add_u32_e32 v40, 0x2400, v22
	v_add_u32_e32 v41, 0x2800, v22
	v_add_u32_e32 v42, 0x2c00, v22
	v_add_u32_e32 v43, 0x3000, v22
	v_add_u32_e32 v44, 0x3400, v22
	v_add_u32_e32 v45, 0x3800, v22
	v_add_u32_e32 v46, 0x3c00, v22
	v_add_u32_e32 v47, 0x400, v23
	v_mov_b32_e32 v48, 6
	s_mov_b32 s54, 0x264000
	s_mov_b32 s55, 0x270000
	s_mov_b32 s56, 0x27c000
	s_mov_b32 s57, 0x288000
	s_mov_b32 s58, 0x294000
	s_mov_b32 s59, 0x2a0000
	s_mov_b32 s60, 0x2ac000
	s_mov_b32 s61, 0x2b8000
	s_mov_b32 s62, 0x2c4000
	s_mov_b32 s63, 0x2d0000
	s_mov_b32 s64, 0x2dc000
	s_mov_b32 s65, 0x2e8000
	s_mov_b32 s66, 0x2f4000
	s_movk_i32 s67, 0x70
	s_movk_i32 s68, 0x7000
	s_mov_b32 s69, 0x2aaaaaab
	s_movk_i32 s70, 0xd000
	s_movk_i32 s71, 0x31ff
	s_mov_b64 s[10:11], 0
	v_readlane_b32 s14, v254, 19
	v_readlane_b32 s15, v254, 20
	v_readlane_b32 s22, v254, 27
	v_readlane_b32 s23, v254, 28
	v_readlane_b32 s26, v254, 31
	v_readlane_b32 s27, v254, 32
	s_branch .LBB0_978
